# C2 contiguous ranges retuned: 5 rows per wave on the fifth-tile workgroups, 9 on the next 1280 waves, 8 on the last 512
# baseline (speedup 1.0000x reference)
; __global__ void __launch_bounds__(NWAVES * 64, 2) mk_fwd(Args args) {
;     ...
;                 for (int m = gw; m < M; m += ngw) {
;                     const bool smp = m >= MP;
;                     const int b = smp ? ((m - MP) >> 5) : (m >> 12), t = smp ? ((m - MP) & 31) : (m & 4095);
.LBB0_498:
	v_readlane_b32 s36, v252, 4
	s_lshl_b64 s[2:3], s[48:49], 2
	v_readlane_b32 s42, v252, 10
	v_readlane_b32 s37, v252, 5
	v_readlane_b32 s43, v252, 11
	s_add_u32 s36, s42, s2
	v_readlane_b32 s38, v252, 6
	s_addc_u32 s37, s43, s3
	s_ashr_i32 s2, s10, 6
	s_lshl_b32 s3, s1, 3
	s_add_i32 s38, s3, s2
	s_cmp_lt_u32 s38, 0x100
	s_cbranch_scc0 .Lc2r_b
	s_mul_i32 s98, s38, 5
	s_add_i32 s99, s98, 4
	s_branch .Lc2r_done
.Lc2r_b:
	s_sub_i32 s99, s38, 0x100
	s_cmp_lt_u32 s99, 0x500
	s_cbranch_scc0 .Lc2r_c
	s_mul_i32 s98, s99, 9
	s_add_i32 s98, s98, 0x500
	s_add_i32 s99, s98, 8
	s_branch .Lc2r_done
.Lc2r_c:
	s_sub_i32 s99, s99, 0x500
	s_lshl_b32 s98, s99, 3
	s_add_i32 s98, s98, 0x3200
	s_add_i32 s99, s98, 7
